# speedup vs baseline: 1.0190x; 1.0059x over previous
; __device__ __forceinline__ void phase_dsa_attn(const Params& p, char* smem) {
;     ...
;         for (int j = lane; j < 256; j += 64) hist[j] = 0;
;         for (int j = lane; j < n; j += 64) atomicAdd(&hist[sc[j] >> 8], 1);
;         {
;           int h0 = hist[lane * 4], h1 = hist[lane * 4 + 1], h2 = hist[lane * 4 + 2], h3 = hist[lane * 4 + 3];
;           int tot = h0 + h1 + h2 + h3;
;           int suf = tot;
; #pragma unroll
;           for (int d = 1; d < 64; d <<= 1) { int o = __shfl_down(suf, d); if (lane + d < 64) suf += o; }
;           const int above = suf - tot;
;           int c3 = above + h3, c2 = c3 + h2, c1 = c2 + h1, c0 = c1 + h0;
;           int myb = -1, myabove = 0;
;           if (above < 256 && c0 >= 256) {
;             if (c3 >= 256) { myb = lane * 4 + 3; myabove = above; }
;             else if (c2 >= 256) { myb = lane * 4 + 2; myabove = c3; }
;             else if (c1 >= 256) { myb = lane * 4 + 1; myabove = c2; }
;             else { myb = lane * 4; myabove = c1; }
;           }
;           const unsigned long long bal = __ballot(myb >= 0);
;           const int src = __ffsll((long long)bal) - 1;
;           thr_hi = __shfl(myb, src);
;           need = 256 - __shfl(myabove, src);
;         }
;         for (int j = lane; j < 256; j += 64) hist[j] = 0;
;         for (int j = lane; j < n; j += 64) { const int k = sc[j]; if ((k >> 8) == thr_hi) atomicAdd(&hist[k & 255], 1); }
.LBB0_351:
	v_lshl_add_u32 v27, s20, 13, v22
	s_waitcnt vmcnt(6)
	ds_write2st64_b32 v23, v101, v101 offset1:1
	ds_write2st64_b32 v23, v101, v101 offset0:2 offset1:3
	v_mad_u32_u24 v28, v12, 6, v27
	v_readfirstlane_b32 s18, v25
	s_add_u32 s18, s18, 1
	s_lshr_b32 s19, s18, 8
.Lmy_tk1_loop:
	ds_read_b64 v[30:31], v28
	v_add_u32_e32 v28, 0x200, v28
	s_sub_u32 s19, s19, 1
	s_waitcnt lgkmcnt(0)
	v_bfe_u32 v29, v30, 8, 8
	v_lshrrev_b32_e32 v30, 24, v30
	v_bfe_u32 v32, v31, 8, 8
	v_lshrrev_b32_e32 v31, 24, v31
	v_lshl_add_u32 v29, v29, 2, v16
	v_lshl_add_u32 v30, v30, 2, v16
	v_lshl_add_u32 v32, v32, 2, v16
	v_lshl_add_u32 v31, v31, 2, v16
	ds_add_u32 v29, v128
	ds_add_u32 v30, v128
	ds_add_u32 v32, v128
	ds_add_u32 v31, v128
	s_cmp_lg_u32 s19, 0
	s_cbranch_scc1 .Lmy_tk1_loop
	s_and_b32 s18, s18, 0xff
	s_cmp_eq_u32 s18, 0
	s_cbranch_scc1 .Lmy_tk1_done
	ds_read_b64 v[30:31], v28
	v_lshlrev_b32_e32 v33, 2, v12
	v_add_u32_e32 v36, 0x13000, v33
	v_add_u32_e32 v37, 1, v33
	v_add_u32_e32 v38, 2, v33
	v_add_u32_e32 v39, 3, v33
	s_waitcnt lgkmcnt(0)
	v_bfe_u32 v29, v30, 8, 8
	v_lshrrev_b32_e32 v30, 24, v30
	v_bfe_u32 v32, v31, 8, 8
	v_lshrrev_b32_e32 v31, 24, v31
	v_lshl_add_u32 v29, v29, 2, v16
	v_lshl_add_u32 v30, v30, 2, v16
	v_lshl_add_u32 v32, v32, 2, v16
	v_lshl_add_u32 v31, v31, 2, v16
	v_cmp_gt_u32_e32 vcc, s18, v33
	v_cmp_gt_u32_e64 s[20:21], s18, v37
	s_nop 1
	v_cndmask_b32_e32 v29, v36, v29, vcc
	v_cndmask_b32_e64 v30, v36, v30, s[20:21]
	v_cmp_gt_u32_e32 vcc, s18, v38
	v_cmp_gt_u32_e64 s[20:21], s18, v39
	s_nop 1
	v_cndmask_b32_e32 v32, v36, v32, vcc
	v_cndmask_b32_e64 v31, v36, v31, s[20:21]
	ds_add_u32 v29, v128
	ds_add_u32 v30, v128
	ds_add_u32 v32, v128
	ds_add_u32 v31, v128
.Lmy_tk1_done:
	s_mov_b64 s[18:19], 0
	s_or_b64 exec, exec, s[18:19]
	s_waitcnt vmcnt(3)
	ds_read_b128 v[40:43], v18
	v_and_b32_e32 v32, 63, v206
	v_cmp_ne_u32_e32 vcc, 63, v32
	s_waitcnt lgkmcnt(0)
	v_add_u32_e32 v29, v41, v40
	v_addc_co_u32_e32 v28, vcc, 0, v206, vcc
	v_add3_u32 v35, v29, v42, v43
	v_lshlrev_b32_e32 v28, 2, v28
	ds_bpermute_b32 v30, v28, v35
	v_cmp_gt_u32_e32 vcc, 62, v32
	s_waitcnt lgkmcnt(0)
	v_cndmask_b32_e64 v30, v30, 0, s[6:7]
	v_cndmask_b32_e64 v29, 0, 2, vcc
	v_add_lshl_u32 v29, v29, v206, 2
	v_add_u32_e32 v31, v30, v35
	ds_bpermute_b32 v33, v29, v31
	v_cmp_gt_u32_e32 vcc, 60, v32
	s_waitcnt lgkmcnt(0)
	v_cndmask_b32_e64 v33, 0, v33, s[8:9]
	v_cndmask_b32_e64 v30, 0, 4, vcc
	v_add_lshl_u32 v30, v30, v206, 2
	v_add_u32_e32 v33, v33, v31
	ds_bpermute_b32 v34, v30, v33
	v_cmp_gt_u32_e32 vcc, 56, v32
	s_waitcnt lgkmcnt(0)
	v_cndmask_b32_e64 v34, 0, v34, s[10:11]
	v_cndmask_b32_e64 v31, 0, 8, vcc
	v_add_lshl_u32 v31, v31, v206, 2
	v_add_u32_e32 v33, v34, v33
	ds_bpermute_b32 v34, v31, v33
	v_cmp_gt_u32_e32 vcc, 48, v32
	s_waitcnt lgkmcnt(0)
	v_cndmask_b32_e64 v34, 0, v34, s[12:13]
	v_cndmask_b32_e64 v32, 0, 16, vcc
	v_add_lshl_u32 v32, v32, v206, 2
	v_add_u32_e32 v34, v34, v33
	ds_bpermute_b32 v36, v32, v34
	v_lshl_or_b32 v33, v206, 2, v129
	s_waitcnt lgkmcnt(0)
	v_cndmask_b32_e64 v36, 0, v36, s[14:15]
	v_add_u32_e32 v36, v36, v34
	ds_bpermute_b32 v37, v33, v36
	v_sub_u32_e32 v35, v36, v35
	v_mov_b32_e32 v34, -1
	s_waitcnt lgkmcnt(0)
	v_cndmask_b32_e64 v36, 0, v37, s[16:17]
	v_add_u32_e32 v35, v35, v36
	v_add_u32_e32 v37, v35, v43
	v_add_u32_e32 v38, v37, v42
	v_add_u32_e32 v39, v38, v41
	v_add_u32_e32 v36, v39, v40
	v_cmp_gt_i32_e32 vcc, s84, v35
	v_cmp_lt_i32_e64 s[18:19], s2, v36
	s_and_b64 s[20:21], vcc, s[18:19]
	v_mov_b32_e32 v36, 0
	s_and_saveexec_b64 s[18:19], s[20:21]
	v_cmp_lt_i32_e32 vcc, s2, v39
	s_nop 1
	v_cndmask_b32_e32 v34, v39, v38, vcc
	v_cndmask_b32_e32 v36, v17, v19, vcc
	v_cmp_lt_i32_e32 vcc, s2, v38
	s_nop 1
	v_cndmask_b32_e32 v34, v34, v37, vcc
	v_cndmask_b32_e32 v38, v36, v20, vcc
	v_cmp_lt_i32_e32 vcc, s2, v37
	s_nop 1
	v_cndmask_b32_e32 v36, v34, v35, vcc
	v_cndmask_b32_e32 v34, v38, v21, vcc
	s_or_b64 exec, exec, s[18:19]
	v_cmp_lt_i32_e32 vcc, -1, v34
	s_ff1_i32_b64 s20, vcc
	s_cmp_lg_u64 vcc, 0
	s_cselect_b32 s20, s20, 63
	v_and_b32_e32 v35, 64, v206
	v_or_b32_e32 v37, s20, v35
	v_lshlrev_b32_e32 v37, 2, v37
	ds_bpermute_b32 v34, v37, v34
	ds_write2st64_b32 v23, v101, v101 offset1:1
	ds_write2st64_b32 v23, v101, v101 offset0:2 offset1:3
	v_mad_u32_u24 v38, v12, 6, v27
	v_lshlrev_b32_e32 v236, 2, v12
	v_add_u32_e32 v237, 0x13000, v236
	v_readfirstlane_b32 s18, v25
	s_add_u32 s18, s18, 1
	s_lshr_b32 s19, s18, 8
	s_waitcnt lgkmcnt(0)
.Lmy_tk2_loop:
	ds_read_b64 v[40:41], v38
	v_add_u32_e32 v38, 0x200, v38
	s_sub_u32 s19, s19, 1
	s_waitcnt lgkmcnt(0)
	v_bfe_u32 v238, v40, 8, 8
	v_lshrrev_b32_e32 v239, 24, v40
	v_bfe_u32 v240, v41, 8, 8
	v_lshrrev_b32_e32 v241, 24, v41
	v_and_b32_e32 v242, 0xff, v40
	v_bfe_u32 v243, v40, 16, 8
	v_and_b32_e32 v244, 0xff, v41
	v_bfe_u32 v245, v41, 16, 8
	v_lshl_add_u32 v242, v242, 2, v16
	v_lshl_add_u32 v243, v243, 2, v16
	v_lshl_add_u32 v244, v244, 2, v16
	v_lshl_add_u32 v245, v245, 2, v16
	v_cmp_eq_u32_e32 vcc, v238, v34
	v_cmp_eq_u32_e64 s[20:21], v239, v34
	s_nop 1
	v_cndmask_b32_e32 v242, v237, v242, vcc
	v_cndmask_b32_e64 v243, v237, v243, s[20:21]
	v_cmp_eq_u32_e32 vcc, v240, v34
	v_cmp_eq_u32_e64 s[20:21], v241, v34
	s_nop 1
	v_cndmask_b32_e32 v244, v237, v244, vcc
	v_cndmask_b32_e64 v245, v237, v245, s[20:21]
	ds_add_u32 v242, v128
	ds_add_u32 v243, v128
	ds_add_u32 v244, v128
	ds_add_u32 v245, v128
	s_cmp_lg_u32 s19, 0
	s_cbranch_scc1 .Lmy_tk2_loop
	s_and_b32 s18, s18, 0xff
	s_cmp_eq_u32 s18, 0
	s_cbranch_scc1 .Lmy_tk2_done
	ds_read_b64 v[40:41], v38
	v_add_u32_e32 v38, 0x200, v38
	s_sub_u32 s19, s19, 1
	s_waitcnt lgkmcnt(0)
	v_bfe_u32 v238, v40, 8, 8
	v_lshrrev_b32_e32 v239, 24, v40
	v_bfe_u32 v240, v41, 8, 8
	v_lshrrev_b32_e32 v241, 24, v41
	v_and_b32_e32 v242, 0xff, v40
	v_bfe_u32 v243, v40, 16, 8
	v_and_b32_e32 v244, 0xff, v41
	v_bfe_u32 v245, v41, 16, 8
	v_lshl_add_u32 v242, v242, 2, v16
	v_lshl_add_u32 v243, v243, 2, v16
	v_lshl_add_u32 v244, v244, 2, v16
	v_lshl_add_u32 v245, v245, 2, v16
	v_mov_b32_e32 v246, v236
	v_cmp_eq_u32_e32 vcc, v238, v34
	v_cmp_gt_u32_e64 s[20:21], s18, v246
	s_nop 1
	s_and_b64 vcc, vcc, s[20:21]
	s_nop 1
	v_cndmask_b32_e32 v242, v237, v242, vcc
	v_add_u32_e32 v246, 1, v236
	v_cmp_eq_u32_e32 vcc, v239, v34
	v_cmp_gt_u32_e64 s[20:21], s18, v246
	s_nop 1
	s_and_b64 vcc, vcc, s[20:21]
	s_nop 1
	v_cndmask_b32_e32 v243, v237, v243, vcc
	v_add_u32_e32 v246, 2, v236
	v_cmp_eq_u32_e32 vcc, v240, v34
	v_cmp_gt_u32_e64 s[20:21], s18, v246
	s_nop 1
	s_and_b64 vcc, vcc, s[20:21]
	s_nop 1
	v_cndmask_b32_e32 v244, v237, v244, vcc
	v_add_u32_e32 v246, 3, v236
	v_cmp_eq_u32_e32 vcc, v241, v34
	v_cmp_gt_u32_e64 s[20:21], s18, v246
	s_nop 1
	s_and_b64 vcc, vcc, s[20:21]
	s_nop 1
	v_cndmask_b32_e32 v245, v237, v245, vcc
	ds_add_u32 v242, v128
	ds_add_u32 v243, v128
	ds_add_u32 v244, v128
	ds_add_u32 v245, v128
.Lmy_tk2_done:
	s_mov_b64 s[18:19], 0
